# v28 + chain-output acquire (counter poll + buffer_inv) once per workgroup instead of per combine chunk: the per-chunk L2 invalidates evicted the K/V tiles of the attention items still running
# speedup vs baseline: 1.0132x; 1.0097x over previous
; DI void phase_combine(const Params& p) {
;   const int lane = threadIdx.x & 63, wave = threadIdx.x >> 6;
;   const unsigned* ofw = (const unsigned*)p.out; const unsigned* obw = (const unsigned*)((const bf16_t*)p.out + (size_t)NTOK * 512);
;   const unsigned* GH = (const unsigned*)(p.ws + WS_GH);
;   bf16_t* OC = (bf16_t*)(p.ws + WS_OCAT);
;   const float w0 = p.hgrn_norm_w[lane * 2], w1 = p.hgrn_norm_w[lane * 2 + 1];
;   for (int tok = blockIdx.x * 8 + wave; tok < NTOK; tok += gridDim.x * 8) {
.Lcq_item:
	s_and_saveexec_b64 s[0:1], s[84:85]
	s_cbranch_execz .Lcq_go
	s_cmp_eq_u32 s32, 1
	s_cbranch_scc1 .Lcq_go
	s_mov_b32 s32, 1
	v_mov_b32_e32 v0, 0
